# cross-segment overlap: the attention epilogue's 8 gate loads are issued during the unit's last K/V tile (into the idle prefetch registers) instead of at the epilogue start
# speedup vs baseline: 1.0046x; 1.0046x over previous
.LBB0_152:
	v_and_b32_e32 v29, 64, v181
	v_readlane_b32 s0, v254, 26
	v_xor_b32_e32 v28, 16, v181
	v_add_u32_e32 v29, 64, v29
	v_readlane_b32 s1, v254, 27
	v_cmp_lt_i32_e32 vcc, v28, v29
	v_xor_b32_e32 v30, 32, v181
	s_mov_b32 s1, s47
	v_cndmask_b32_e32 v28, v181, v28, vcc
	v_cmp_lt_i32_e32 vcc, v30, v29
	s_lshl_b64 s[0:1], s[0:1], 1
	v_readlane_b32 s4, v253, 33
	v_cndmask_b32_e32 v29, v181, v30, vcc
	v_lshl_add_u64 v[30:31], v[126:127], 0, s[0:1]
	v_readlane_b32 s5, v253, 34
	s_add_u32 s0, s4, s0
	s_addc_u32 s1, s5, s1
	v_mov_b64_e32 v[32:33], s[0:1]
	v_mad_i64_i32 v[34:35], s[0:1], v204, s70, v[32:33]
	v_lshlrev_b32_e32 v144, 1, v122
	v_lshl_add_u64 v[32:33], v[30:31], 0, v[144:145]
	s_mov_b64 s[0:1], 0x2400
	v_lshl_add_u64 v[30:31], v[32:33], 0, s[0:1]
	s_movk_i32 s0, 0x2000
	v_add_co_u32_e32 v32, vcc, s0, v32
	v_lshlrev_b32_e32 v28, 2, v28
	s_nop 0
	v_addc_co_u32_e32 v33, vcc, 0, v33, vcc
	ds_bpermute_b32 v28, v28, v205
	v_lshlrev_b32_e32 v29, 2, v29
	v_readlane_b32 s96, v254, 21
	v_readlane_b32 s97, v254, 22
	v_readlane_b32 s98, v254, 24
	s_waitcnt lgkmcnt(0)
	v_add_f32_e32 v28, v205, v28
	ds_bpermute_b32 v146, v29, v28
	v_readlane_b32 s99, v254, 23
	v_readlane_b32 s97, v254, 25
	s_mov_b64 s[38:39], 0
	s_waitcnt vmcnt(0)
	v_mov_b64_e32 v[32:33], v[14:15]
	v_lshlrev_b32_e32 v29, 16, v32
	v_mul_f32_e32 v37, 0xbfb8aa3b, v29
	v_exp_f32_e32 v37, v37
	v_and_b32_e32 v32, 0xffff0000, v32
	v_lshlrev_b32_e32 v36, 16, v33
	v_and_b32_e32 v33, 0xffff0000, v33
	v_add_f32_e32 v37, 1.0, v37
	s_nop 0
	v_rcp_f32_e32 v38, v37
	s_nop 0
	v_mul_f32_e32 v37, v29, v38
	v_mul_f32_e32 v29, 0xbfb8aa3b, v32
	v_exp_f32_e32 v29, v29
	s_nop 0
	v_add_f32_e32 v29, 1.0, v29
	s_nop 0
	v_rcp_f32_e32 v38, v29
	s_nop 0
	v_mul_f32_e32 v38, v32, v38
	v_mul_f32_e32 v29, 0xbfb8aa3b, v36
	v_exp_f32_e32 v29, v29
	s_waitcnt lgkmcnt(0)
	v_pk_add_f32 v[28:29], v[28:29], v[146:147]
	s_nop 0
	s_nop 0
	v_rcp_f32_e32 v32, v29
	s_nop 0
	v_mul_f32_e32 v29, v36, v32
	s_nop 0
	v_rcp_f32_e32 v32, v28
	s_nop 0
	v_mul_f32_e32 v32, 1.0, v32
	v_mul_f32_e32 v28, v76, v32
	v_mul_f32_e32 v28, v28, v37
	v_mul_f32_e32 v37, 0xbfb8aa3b, v33
	v_exp_f32_e32 v37, v37
	v_mul_f32_e32 v36, v77, v32
	v_mul_f32_e32 v36, v36, v38
	v_cvt_pk_bf16_f32 v36, v28, v36
	v_add_f32_e32 v37, 1.0, v37
	v_mul_f32_e32 v28, v78, v32
	v_mul_f32_e32 v28, v28, v29
	v_mul_f32_e32 v29, v79, v32
	v_rcp_f32_e32 v38, v37
	s_nop 0
	v_mul_f32_e32 v33, v33, v38
	v_mul_f32_e32 v29, v29, v33
	v_cvt_pk_bf16_f32 v37, v28, v29
	v_lshl_add_u64 v[28:29], v[34:35], 0, v[144:145]
	v_mov_b64_e32 v[34:35], v[0:1]
	v_mul_f32_e32 v24, v24, v32
	global_store_dwordx2 v[28:29], v[36:37], off
	v_mul_f32_e32 v37, v72, v32
	v_mul_f32_e32 v25, v25, v32
	v_mul_f32_e32 v20, v20, v32
	v_mul_f32_e32 v21, v21, v32
	v_mul_f32_e32 v16, v16, v32
	v_mul_f32_e32 v17, v17, v32
	v_lshlrev_b32_e32 v33, 16, v34
	v_mul_f32_e32 v38, 0xbfb8aa3b, v33
	v_exp_f32_e32 v38, v38
	v_and_b32_e32 v34, 0xffff0000, v34
	v_lshlrev_b32_e32 v36, 16, v35
	v_and_b32_e32 v35, 0xffff0000, v35
	v_add_f32_e32 v38, 1.0, v38
	s_nop 0
	v_rcp_f32_e32 v39, v38
	s_nop 0
	v_mul_f32_e32 v33, v33, v39
	v_mul_f32_e32 v38, 0xbfb8aa3b, v34
	v_exp_f32_e32 v38, v38
	v_mul_f32_e32 v33, v37, v33
	v_mul_f32_e32 v37, v73, v32
	v_add_f32_e32 v38, 1.0, v38
	s_nop 0
	v_rcp_f32_e32 v39, v38
	s_nop 0
	v_mul_f32_e32 v34, v34, v39
	v_mul_f32_e32 v34, v37, v34
	v_mul_f32_e32 v37, 0xbfb8aa3b, v36
	v_exp_f32_e32 v37, v37
	v_cvt_pk_bf16_f32 v34, v33, v34
	v_mul_f32_e32 v33, v74, v32
	v_add_f32_e32 v37, 1.0, v37
	s_nop 0
	v_rcp_f32_e32 v38, v37
	s_nop 0
	v_mul_f32_e32 v36, v36, v38
	v_mul_f32_e32 v37, 0xbfb8aa3b, v35
	v_exp_f32_e32 v37, v37
	v_mul_f32_e32 v33, v33, v36
	v_mul_f32_e32 v36, v75, v32
	v_add_f32_e32 v37, 1.0, v37
	s_nop 0
	v_rcp_f32_e32 v38, v37
	s_nop 0
	v_mul_f32_e32 v35, v35, v38
	v_mul_f32_e32 v35, v36, v35
	v_cvt_pk_bf16_f32 v35, v33, v35
	global_store_dwordx2 v[28:29], v[34:35], off offset:32
	v_mov_b64_e32 v[34:35], v[2:3]
	v_mul_f32_e32 v37, v68, v32
	v_lshlrev_b32_e32 v33, 16, v34
	v_mul_f32_e32 v38, 0xbfb8aa3b, v33
	v_exp_f32_e32 v38, v38
	v_and_b32_e32 v34, 0xffff0000, v34
	v_lshlrev_b32_e32 v36, 16, v35
	v_and_b32_e32 v35, 0xffff0000, v35
	v_add_f32_e32 v38, 1.0, v38
	s_nop 0
	v_rcp_f32_e32 v39, v38
	s_nop 0
	v_mul_f32_e32 v33, v33, v39
	v_mul_f32_e32 v38, 0xbfb8aa3b, v34
	v_exp_f32_e32 v38, v38
	v_mul_f32_e32 v33, v37, v33
	v_mul_f32_e32 v37, v69, v32
	v_add_f32_e32 v38, 1.0, v38
	s_nop 0
	v_rcp_f32_e32 v39, v38
	s_nop 0
	v_mul_f32_e32 v34, v34, v39
	v_mul_f32_e32 v34, v37, v34
	v_mul_f32_e32 v37, 0xbfb8aa3b, v36
	v_exp_f32_e32 v37, v37
	v_cvt_pk_bf16_f32 v34, v33, v34
	v_mul_f32_e32 v33, v70, v32
	v_add_f32_e32 v37, 1.0, v37
	s_nop 0
	v_rcp_f32_e32 v38, v37
	s_nop 0
	v_mul_f32_e32 v36, v36, v38
	v_mul_f32_e32 v37, 0xbfb8aa3b, v35
	v_exp_f32_e32 v37, v37
	v_mul_f32_e32 v33, v33, v36
	v_mul_f32_e32 v36, v71, v32
	v_add_f32_e32 v37, 1.0, v37
	s_nop 0
	v_rcp_f32_e32 v38, v37
	s_nop 0
	v_mul_f32_e32 v35, v35, v38
	v_mul_f32_e32 v35, v36, v35
	v_cvt_pk_bf16_f32 v35, v33, v35
	global_store_dwordx2 v[28:29], v[34:35], off offset:64
	v_mov_b64_e32 v[34:35], v[4:5]
	v_mul_f32_e32 v37, v64, v32
	v_lshlrev_b32_e32 v33, 16, v34
	v_mul_f32_e32 v38, 0xbfb8aa3b, v33
	v_exp_f32_e32 v38, v38
	v_and_b32_e32 v34, 0xffff0000, v34
	v_lshlrev_b32_e32 v36, 16, v35
	v_and_b32_e32 v35, 0xffff0000, v35
	v_add_f32_e32 v38, 1.0, v38
	s_nop 0
	v_rcp_f32_e32 v39, v38
	s_nop 0
	v_mul_f32_e32 v33, v33, v39
	v_mul_f32_e32 v38, 0xbfb8aa3b, v34
	v_exp_f32_e32 v38, v38
	v_mul_f32_e32 v33, v37, v33
	v_mul_f32_e32 v37, v65, v32
	v_add_f32_e32 v38, 1.0, v38
	s_nop 0
	v_rcp_f32_e32 v39, v38
	s_nop 0
	v_mul_f32_e32 v34, v34, v39
	v_mul_f32_e32 v34, v37, v34
	v_mul_f32_e32 v37, 0xbfb8aa3b, v36
	v_exp_f32_e32 v37, v37
	v_cvt_pk_bf16_f32 v34, v33, v34
	v_mul_f32_e32 v33, v66, v32
	v_add_f32_e32 v37, 1.0, v37
	s_nop 0
	v_rcp_f32_e32 v38, v37
	s_nop 0
	v_mul_f32_e32 v36, v36, v38
	v_mul_f32_e32 v37, 0xbfb8aa3b, v35
	v_exp_f32_e32 v37, v37
	v_mul_f32_e32 v33, v33, v36
	v_mul_f32_e32 v36, v67, v32
	v_add_f32_e32 v37, 1.0, v37
	s_nop 0
	v_rcp_f32_e32 v38, v37
	s_nop 0
	v_mul_f32_e32 v35, v35, v38
	v_mul_f32_e32 v35, v36, v35
	v_cvt_pk_bf16_f32 v35, v33, v35
	global_store_dwordx2 v[28:29], v[34:35], off offset:96
	v_mov_b64_e32 v[34:35], v[6:7]
	v_mul_f32_e32 v37, v60, v32
	v_lshlrev_b32_e32 v33, 16, v34
	v_mul_f32_e32 v38, 0xbfb8aa3b, v33
	v_exp_f32_e32 v38, v38
	v_and_b32_e32 v34, 0xffff0000, v34
	v_lshlrev_b32_e32 v36, 16, v35
	v_and_b32_e32 v35, 0xffff0000, v35
	v_add_f32_e32 v38, 1.0, v38
	s_nop 0
	v_rcp_f32_e32 v39, v38
	s_nop 0
	v_mul_f32_e32 v33, v33, v39
	v_mul_f32_e32 v38, 0xbfb8aa3b, v34
	v_exp_f32_e32 v38, v38
	v_mul_f32_e32 v33, v37, v33
	v_mul_f32_e32 v37, v61, v32
	v_add_f32_e32 v38, 1.0, v38
	s_nop 0
	v_rcp_f32_e32 v39, v38
	s_nop 0
	v_mul_f32_e32 v34, v34, v39
	v_mul_f32_e32 v34, v37, v34
	v_mul_f32_e32 v37, 0xbfb8aa3b, v36
	v_exp_f32_e32 v37, v37
	v_cvt_pk_bf16_f32 v34, v33, v34
	v_mul_f32_e32 v33, v62, v32
	v_add_f32_e32 v37, 1.0, v37
	s_nop 0
	v_rcp_f32_e32 v38, v37
	s_nop 0
	v_mul_f32_e32 v36, v36, v38
	v_mul_f32_e32 v37, 0xbfb8aa3b, v35
	v_exp_f32_e32 v37, v37
	v_mul_f32_e32 v33, v33, v36
	v_mul_f32_e32 v36, v63, v32
	v_add_f32_e32 v37, 1.0, v37
	s_nop 0
	v_rcp_f32_e32 v38, v37
	s_nop 0
	v_mul_f32_e32 v35, v35, v38
	v_mul_f32_e32 v35, v36, v35
	v_cvt_pk_bf16_f32 v35, v33, v35
	global_store_dwordx2 v[28:29], v[34:35], off offset:128
	v_mov_b64_e32 v[34:35], v[8:9]
	v_lshlrev_b32_e32 v33, 16, v34
	v_mul_f32_e32 v37, 0xbfb8aa3b, v33
	v_exp_f32_e32 v37, v37
	v_and_b32_e32 v34, 0xffff0000, v34
	v_lshlrev_b32_e32 v36, 16, v35
	v_and_b32_e32 v35, 0xffff0000, v35
	v_add_f32_e32 v37, 1.0, v37
	s_nop 0
	v_rcp_f32_e32 v38, v37
	s_nop 0
	v_mul_f32_e32 v33, v33, v38
	v_mul_f32_e32 v24, v24, v33
	v_mul_f32_e32 v33, 0xbfb8aa3b, v34
	v_exp_f32_e32 v33, v33
	s_nop 0
	v_add_f32_e32 v33, 1.0, v33
	s_nop 0
	v_rcp_f32_e32 v37, v33
	s_nop 0
	v_mul_f32_e32 v33, v34, v37
	v_mul_f32_e32 v25, v25, v33
	v_cvt_pk_bf16_f32 v24, v24, v25
	v_mul_f32_e32 v25, v26, v32
	v_mul_f32_e32 v26, 0xbfb8aa3b, v36
	v_exp_f32_e32 v26, v26
	s_nop 0
	v_add_f32_e32 v26, 1.0, v26
	s_nop 0
	v_rcp_f32_e32 v33, v26
	s_nop 0
	v_mul_f32_e32 v26, v36, v33
	v_mul_f32_e32 v25, v25, v26
	v_mul_f32_e32 v26, v27, v32
	v_mul_f32_e32 v27, 0xbfb8aa3b, v35
	v_exp_f32_e32 v27, v27
	s_nop 0
	v_add_f32_e32 v27, 1.0, v27
	s_nop 0
	v_rcp_f32_e32 v33, v27
	s_nop 0
	v_mul_f32_e32 v27, v35, v33
	v_mul_f32_e32 v26, v26, v27
	v_cvt_pk_bf16_f32 v25, v25, v26
	global_store_dwordx2 v[28:29], v[24:25], off offset:160
	v_mov_b64_e32 v[24:25], v[10:11]
	v_lshlrev_b32_e32 v26, 16, v24
	v_mul_f32_e32 v33, 0xbfb8aa3b, v26
	v_exp_f32_e32 v33, v33
	v_and_b32_e32 v24, 0xffff0000, v24
	v_lshlrev_b32_e32 v27, 16, v25
	v_and_b32_e32 v25, 0xffff0000, v25
	v_add_f32_e32 v33, 1.0, v33
	s_nop 0
	v_rcp_f32_e32 v34, v33
	s_nop 0
	v_mul_f32_e32 v26, v26, v34
	v_mul_f32_e32 v20, v20, v26
	v_mul_f32_e32 v26, 0xbfb8aa3b, v24
	v_exp_f32_e32 v26, v26
	s_nop 0
	v_add_f32_e32 v26, 1.0, v26
	s_nop 0
	v_rcp_f32_e32 v33, v26
	s_nop 0
	v_mul_f32_e32 v24, v24, v33
	v_mul_f32_e32 v21, v21, v24
	v_cvt_pk_bf16_f32 v20, v20, v21
	v_mul_f32_e32 v21, v22, v32
	v_mul_f32_e32 v22, 0xbfb8aa3b, v27
	v_exp_f32_e32 v22, v22
	s_nop 0
	v_add_f32_e32 v22, 1.0, v22
	s_nop 0
	v_rcp_f32_e32 v24, v22
	s_nop 0
	v_mul_f32_e32 v22, v27, v24
	v_mul_f32_e32 v21, v21, v22
	v_mul_f32_e32 v22, v23, v32
	v_mul_f32_e32 v23, 0xbfb8aa3b, v25
	v_exp_f32_e32 v23, v23
	s_nop 0
	v_add_f32_e32 v23, 1.0, v23
	s_nop 0
	v_rcp_f32_e32 v24, v23
	s_nop 0
	v_mul_f32_e32 v23, v25, v24
	v_mul_f32_e32 v22, v22, v23
	v_cvt_pk_bf16_f32 v21, v21, v22
	global_store_dwordx2 v[28:29], v[20:21], off offset:192
	v_mov_b64_e32 v[20:21], v[12:13]
	v_lshlrev_b32_e32 v22, 16, v20
	v_mul_f32_e32 v24, 0xbfb8aa3b, v22
	v_exp_f32_e32 v24, v24
	v_and_b32_e32 v20, 0xffff0000, v20
	v_lshlrev_b32_e32 v23, 16, v21
	v_and_b32_e32 v21, 0xffff0000, v21
	v_add_f32_e32 v24, 1.0, v24
	s_nop 0
	v_rcp_f32_e32 v25, v24
	s_nop 0
	v_mul_f32_e32 v22, v22, v25
	v_mul_f32_e32 v16, v16, v22
	v_mul_f32_e32 v22, 0xbfb8aa3b, v20
	v_exp_f32_e32 v22, v22
	s_nop 0
	v_add_f32_e32 v22, 1.0, v22
	s_nop 0
	v_rcp_f32_e32 v24, v22
	s_nop 0
	v_mul_f32_e32 v20, v20, v24
	v_mul_f32_e32 v17, v17, v20
	v_cvt_pk_bf16_f32 v16, v16, v17
	v_mul_f32_e32 v17, v18, v32
	v_mul_f32_e32 v18, 0xbfb8aa3b, v23
	v_exp_f32_e32 v18, v18
	s_nop 0
	v_add_f32_e32 v18, 1.0, v18
	s_nop 0
	v_rcp_f32_e32 v20, v18
	s_nop 0
	v_mul_f32_e32 v18, v23, v20
	v_mul_f32_e32 v17, v17, v18
	v_mul_f32_e32 v18, v19, v32
	v_mul_f32_e32 v19, 0xbfb8aa3b, v21
	v_exp_f32_e32 v19, v19
	s_nop 0
	v_add_f32_e32 v19, 1.0, v19
	s_nop 0
	v_rcp_f32_e32 v20, v19
	s_nop 0
	v_mul_f32_e32 v19, v21, v20
	v_mul_f32_e32 v18, v18, v19
	v_cvt_pk_bf16_f32 v17, v17, v18
	global_store_dwordx2 v[28:29], v[16:17], off offset:224

.LBB0_226:
	global_load_dwordx4 v[44:47], v[44:45], off
	s_nop 0
	global_load_dwordx4 v[48:51], v[48:49], off
	global_load_dwordx4 v[52:55], v[52:53], off
	global_load_dwordx4 v[56:59], v[56:57], off
	s_branch .LBB0_227
.Lgate_early:
	v_readlane_b32 s34, v254, 26
	v_lshlrev_b32_e32 v46, 1, v122
	v_mov_b32_e32 v47, v145
	s_mov_b32 s35, s47
	s_lshl_b64 s[34:35], s[34:35], 1
	v_lshl_add_u64 v[44:45], v[126:127], 0, s[34:35]
	s_mov_b64 s[34:35], 0x2400
	v_lshl_add_u64 v[44:45], v[44:45], 0, v[46:47]
	v_lshl_add_u64 v[44:45], v[44:45], 0, s[34:35]
	global_load_dwordx2 v[14:15], v[44:45], off nt
	global_load_dwordx2 v[0:1], v[44:45], off offset:32 nt
	global_load_dwordx2 v[2:3], v[44:45], off offset:64 nt
	global_load_dwordx2 v[4:5], v[44:45], off offset:96 nt
	global_load_dwordx2 v[6:7], v[44:45], off offset:128 nt
	global_load_dwordx2 v[8:9], v[44:45], off offset:160 nt
	global_load_dwordx2 v[10:11], v[44:45], off offset:192 nt
	global_load_dwordx2 v[12:13], v[44:45], off offset:224 nt
